# out-proj K loop: static priority raise for waves 4-7 (as in the in-proj loop)
# baseline (speedup 1.0000x reference)
; template <int MODE>
; DI void gemm_phase(const Params& p, int layer, int hf, unsigned char* shmc, int tid) {
;     ...
;     const bf16_t* gA = (MODE == 0) ? A + (size_t)(brow >> 7) * nt * 4096 : A + (size_t)brow * lda; const bf16_t* gB = Bt + (size_t)(bcol >> 7) * nt * 4096;
;     ...
;     if (!pre) { STAGE_ALL(0, 0); STAGE_ALL(1, 1); }
;     STAGE_ALL(2, 2);
.LBB0_692:
	v_mov_b32_e32 v2, v169
	s_lshl_b32 s15, s6, 8
	s_mul_i32 s4, s6, 0x340000
	s_mul_hi_i32 s5, s15, 0x3400
	v_lshlrev_b32_e32 v0, 4, v2
	v_and_b32_e32 v1, 32, v2
	s_add_u32 s4, s35, s4
	v_readlane_b32 s6, v253, 40
	v_add_u32_e32 v4, 32, v0
	v_bfe_u32 v3, v2, 2, 23
	v_bitop3_b32 v0, v0, v1, 48 bitop3:0x6c
	s_addc_u32 s5, s6, s5
	s_lshl_b32 s6, s14, 1
	v_lshrrev_b32_e32 v0, 1, v0
	v_mul_u32_u24_e32 v1, 0x1a00, v3
	s_ashr_i32 s7, s6, 31
	v_or_b32_e32 v0, v1, v0
	s_lshl_b64 s[6:7], s[6:7], 19
	v_readlane_b32 s8, v254, 41
	v_ashrrev_i32_e32 v1, 31, v0
	v_add_u32_e32 v5, 0x4000, v4
	v_readfirstlane_b32 s10, v4
	s_add_u32 s8, s8, s6
	v_readlane_b32 s9, v254, 42
	v_lshl_add_u64 v[0:1], v[0:1], 1, s[4:5]
	v_lshlrev_b32_e32 v2, 3, v2
	s_mov_b32 m0, s10
	v_readfirstlane_b32 s10, v5
	s_addc_u32 s9, s9, s7
	v_ashrrev_i32_e32 v3, 31, v2
	global_load_lds_dwordx4 v[0:1], off
	s_mov_b32 m0, s10
	s_mov_b64 s[10:11], 0x1a0000
	v_add_u32_e32 v5, 0x2000, v4
	v_lshl_add_u64 v[2:3], v[2:3], 1, s[8:9]
	v_lshl_add_u64 v[0:1], v[0:1], 0, s[10:11]
	v_readfirstlane_b32 s10, v5
	global_load_lds_dwordx4 v[2:3], off
	s_mov_b32 m0, s10
	s_mov_b64 s[10:11], 0x80000
	global_load_lds_dwordx4 v[0:1], off
	v_lshl_add_u64 v[0:1], v[2:3], 0, s[10:11]
	v_add_u32_e32 v2, 0x6000, v4
	s_mov_b32 s16, 0
	v_readfirstlane_b32 s10, v2
	s_mov_b32 m0, s10
	v_mov_b32_e32 v2, v169
	global_load_lds_dwordx4 v[0:1], off
	s_movk_i32 s17, 0x60
	v_lshlrev_b32_e32 v0, 4, v2
	v_and_b32_e32 v1, 32, v2
	v_add_u32_e32 v6, 32, v0
	v_bfe_u32 v3, v2, 2, 23
	v_bitop3_b32 v0, v0, v1, 48 bitop3:0x6c
	v_lshrrev_b32_e32 v0, 1, v0
	v_mul_u32_u24_e32 v1, 0x1a00, v3
	v_or_b32_e32 v0, v1, v0
	v_add_u32_e32 v7, 0x8000, v6
	v_ashrrev_i32_e32 v1, 31, v0
	v_lshlrev_b32_e32 v2, 3, v2
	v_lshl_add_u64 v[0:1], v[0:1], 1, s[4:5]
	v_ashrrev_i32_e32 v3, 31, v2
	v_readfirstlane_b32 s10, v7
	v_add_u32_e32 v8, 0xc000, v6
	v_lshl_add_u64 v[4:5], v[0:1], 0, 64
	s_mov_b32 m0, s10
	v_lshl_add_u64 v[2:3], v[2:3], 1, s[8:9]
	s_mov_b64 s[10:11], 0x2000
	global_load_lds_dwordx4 v[4:5], off
	v_lshl_add_u64 v[4:5], v[2:3], 0, s[10:11]
	v_readfirstlane_b32 s10, v8
	s_mov_b32 m0, s10
	s_mov_b64 s[10:11], 0x1a0040
	global_load_lds_dwordx4 v[4:5], off
	v_add_u32_e32 v4, 0xa000, v6
	v_lshl_add_u64 v[0:1], v[0:1], 0, s[10:11]
	v_readfirstlane_b32 s10, v4
	s_mov_b32 m0, s10
	s_mov_b64 s[10:11], 0x82000
	global_load_lds_dwordx4 v[0:1], off
	v_lshl_add_u64 v[0:1], v[2:3], 0, s[10:11]
	v_add_u32_e32 v2, 0xe000, v6
	s_mov_b32 s18, 0x18000
	v_readfirstlane_b32 s10, v2
	s_mov_b32 m0, s10
	v_mov_b32_e32 v2, v169
	global_load_lds_dwordx4 v[0:1], off
	v_readlane_b32 s10, v253, 62
	v_lshlrev_b32_e32 v0, 4, v2
	v_and_b32_e32 v1, 32, v2
	v_add_u32_e32 v6, s10, v0
	v_bfe_u32 v3, v2, 2, 23
	v_bitop3_b32 v0, v0, v1, 48 bitop3:0x6c
	v_lshrrev_b32_e32 v0, 1, v0
	v_mul_u32_u24_e32 v1, 0x1a00, v3
	v_or_b32_e32 v0, v1, v0
	v_ashrrev_i32_e32 v1, 31, v0
	v_lshl_add_u64 v[0:1], v[0:1], 1, s[4:5]
	v_lshlrev_b32_e32 v2, 3, v2
	s_mov_b64 s[10:11], 0x80
	v_ashrrev_i32_e32 v3, 31, v2
	v_lshl_add_u64 v[4:5], v[0:1], 0, s[10:11]
	v_readfirstlane_b32 s10, v6
	v_add_u32_e32 v7, 0x4000, v6
	s_mov_b32 m0, s10
	v_lshl_add_u64 v[2:3], v[2:3], 1, s[8:9]
	s_mov_b64 s[8:9], 0x4000
	global_load_lds_dwordx4 v[4:5], off
	v_lshl_add_u64 v[4:5], v[2:3], 0, s[8:9]
	v_readfirstlane_b32 s8, v7
	s_mov_b32 m0, s8
	s_mov_b64 s[8:9], 0x1a0080
	global_load_lds_dwordx4 v[4:5], off
	v_add_u32_e32 v4, 0x2000, v6
	v_lshl_add_u64 v[0:1], v[0:1], 0, s[8:9]
	v_readfirstlane_b32 s8, v4
	s_mov_b32 m0, s8
	s_mov_b64 s[8:9], 0x84000
	global_load_lds_dwordx4 v[0:1], off
	v_lshl_add_u64 v[0:1], v[2:3], 0, s[8:9]
	v_add_u32_e32 v2, 0x6000, v6
	s_nop 0
	v_readfirstlane_b32 s8, v2
	s_mov_b32 m0, s8
	v_readlane_b32 s8, v253, 60
	global_load_lds_dwordx4 v[0:1], off
	v_mov_b32_e32 v0, 0
	v_readlane_b32 s9, v253, 61
	v_mov_b32_e32 v1, v0
	v_mov_b32_e32 v2, v0
	v_mov_b32_e32 v3, v0
	v_mov_b32_e32 v4, v0
	v_mov_b32_e32 v5, v0
; #define WAIT_V(n) asm volatile("s_waitcnt vmcnt(" #n ")" ::: "memory")
; #define BAR __builtin_amdgcn_s_barrier()
; #define LDA_(dst, ai) _Pragma("unroll") for (int m = 0; m < 4; ++m) dst[m] = *(const bf16x8*)(sb + (ai) * 8192 + la0 + m * 1024)
; #define LDB_(dst) _Pragma("unroll") for (int bj = 0; bj < 2; ++bj) _Pragma("unroll") for (int n = 0; n < 2; ++n) dst[bj][n] = *(const bf16x8*)(sb + 16384 + bj * 8192 + lb0 + n * 1024)
; template <int MODE>
; DI void gemm_phase(const Params& p, int layer, int hf, unsigned char* shmc, int tid) {
;     ...
; #pragma unroll
;     for (int a = 0; a < 2; ++a)
; #pragma unroll
;       for (int b = 0; b < 2; ++b)
; #pragma unroll
;         for (int m = 0; m < 4; ++m)
; #pragma unroll
;           for (int n = 0; n < 2; ++n) acc[a][b][m][n] = (f32x4){0.f, 0.f, 0.f, 0.f};
;     ...
;     for (int kt = 0; kt < nt; ++kt) {
;       const int rem = nt - 1 - kt;
;       if (rem >= 2) WAIT_V(8); else if (rem == 1) WAIT_V(4); else WAIT_V(0);
;       BAR;
;       const unsigned char* sb = shmc + (kt & 3) * 32768;
;     ...
;       {
;         bf16x8 b0[2][2], a0[4], a1[4];
;         LDB_(b0); LDA_(a0, 0);
	v_mov_b32_e32 v6, v0
	v_mov_b32_e32 v7, v0
	v_mov_b32_e32 v8, v0
	v_mov_b32_e32 v9, v0
	v_mov_b32_e32 v10, v0
	v_mov_b32_e32 v11, v0
	v_mov_b32_e32 v12, v0
	v_mov_b32_e32 v13, v0
	v_mov_b32_e32 v14, v0
	v_mov_b32_e32 v15, v0
	v_mov_b32_e32 v64, v0
	v_mov_b32_e32 v65, v0
	v_mov_b32_e32 v66, v0
	v_mov_b32_e32 v67, v0
	v_mov_b32_e32 v68, v0
	v_mov_b32_e32 v69, v0
	v_mov_b32_e32 v70, v0
	v_mov_b32_e32 v71, v0
	v_mov_b32_e32 v72, v0
	v_mov_b32_e32 v73, v0
	v_mov_b32_e32 v74, v0
	v_mov_b32_e32 v75, v0
	v_mov_b32_e32 v76, v0
	v_mov_b32_e32 v77, v0
	v_mov_b32_e32 v78, v0
	v_mov_b32_e32 v79, v0
	v_mov_b32_e32 v80, v0
	v_mov_b32_e32 v81, v0
	v_mov_b32_e32 v82, v0
	v_mov_b32_e32 v83, v0
	v_mov_b32_e32 v84, v0
	v_mov_b32_e32 v85, v0
	v_mov_b32_e32 v86, v0
	v_mov_b32_e32 v87, v0
	v_mov_b32_e32 v92, v0
	v_mov_b32_e32 v93, v0
	v_mov_b32_e32 v94, v0
	v_mov_b32_e32 v95, v0
	v_mov_b32_e32 v100, v0
	v_mov_b32_e32 v101, v0
	v_mov_b32_e32 v102, v0
	v_mov_b32_e32 v103, v0
	v_mov_b32_e32 v88, v0
	v_mov_b32_e32 v89, v0
	v_mov_b32_e32 v90, v0
	v_mov_b32_e32 v91, v0
	v_mov_b32_e32 v96, v0
	v_mov_b32_e32 v97, v0
	v_mov_b32_e32 v98, v0
	v_mov_b32_e32 v99, v0
	v_mov_b32_e32 v104, v0
	v_mov_b32_e32 v105, v0
	v_mov_b32_e32 v106, v0
	v_mov_b32_e32 v107, v0
	v_mov_b32_e32 v108, v0
	v_mov_b32_e32 v109, v0
	v_mov_b32_e32 v110, v0
	v_mov_b32_e32 v111, v0
	v_mov_b32_e32 v112, v0
	v_mov_b32_e32 v113, v0
	v_mov_b32_e32 v114, v0
	v_mov_b32_e32 v115, v0
	v_mov_b32_e32 v116, v0
	v_mov_b32_e32 v117, v0
	v_mov_b32_e32 v118, v0
	v_mov_b32_e32 v119, v0
	v_mov_b32_e32 v120, v0
	v_mov_b32_e32 v121, v0
	v_mov_b32_e32 v122, v0
	v_mov_b32_e32 v123, v0
	v_mov_b32_e32 v124, v0
	v_mov_b32_e32 v125, v0
	v_mov_b32_e32 v126, v0
	v_mov_b32_e32 v127, v0
	v_mov_b32_e32 v16, v0
	v_mov_b32_e32 v17, v0
	v_mov_b32_e32 v18, v0
	v_mov_b32_e32 v19, v0
	v_mov_b32_e32 v20, v0
	v_mov_b32_e32 v21, v0
	v_mov_b32_e32 v22, v0
	v_mov_b32_e32 v23, v0
	v_mov_b32_e32 v24, v0
	v_mov_b32_e32 v25, v0
	v_mov_b32_e32 v26, v0
	v_mov_b32_e32 v27, v0
	v_mov_b32_e32 v28, v0
	v_mov_b32_e32 v29, v0
	v_mov_b32_e32 v30, v0
	v_mov_b32_e32 v31, v0
	v_mov_b32_e32 v32, v0
	v_mov_b32_e32 v33, v0
	v_mov_b32_e32 v34, v0
	v_mov_b32_e32 v35, v0
	v_mov_b32_e32 v36, v0
	v_mov_b32_e32 v37, v0
	v_mov_b32_e32 v38, v0
	v_mov_b32_e32 v39, v0
	v_mov_b32_e32 v40, v0
	v_mov_b32_e32 v41, v0
	v_mov_b32_e32 v42, v0
	v_mov_b32_e32 v43, v0
	v_mov_b32_e32 v44, v0
	v_mov_b32_e32 v45, v0
	v_mov_b32_e32 v46, v0
	v_mov_b32_e32 v47, v0
	v_mov_b32_e32 v48, v0
	v_mov_b32_e32 v49, v0
	v_mov_b32_e32 v50, v0
	v_mov_b32_e32 v51, v0
	v_mov_b32_e32 v52, v0
	v_mov_b32_e32 v53, v0
	v_mov_b32_e32 v54, v0
	v_mov_b32_e32 v55, v0
	v_mov_b32_e32 v56, v0
	v_mov_b32_e32 v57, v0
	v_mov_b32_e32 v58, v0
	v_mov_b32_e32 v59, v0
	v_mov_b32_e32 v60, v0
	v_mov_b32_e32 v61, v0
	v_mov_b32_e32 v62, v0
	v_mov_b32_e32 v63, v0
	v_lshlrev_b32_e32 v183, 4, v169
	v_and_b32_e32 v182, 32, v169
	v_bitop3_b32 v182, v183, v182, 48 bitop3:0x6c
	v_lshrrev_b32_e32 v184, 2, v169
	v_lshrrev_b32_e32 v182, 1, v182
	v_mul_u32_u24_e32 v184, 0x1a00, v184
	v_readfirstlane_b32 s29, v183
	v_add_u32_e32 v182, v182, v184
	v_lshlrev_b32_e32 v182, 1, v182
	v_add_u32_e32 v184, 32, v173
	v_add_u32_e32 v185, 0x10020, v173
	v_add3_u32 v186, v174, v172, 32
	s_add_u32 s98, s4, 0xc0
	s_addc_u32 s99, s5, 0
	s_add_u32 s100, s8, s6
	s_addc_u32 s101, s9, s7
	v_add_u32_e32 v187, 0x10000, v186
	s_add_i32 s29, s29, 32
	s_mov_b32 s28, 0
	v_readfirstlane_b32 s0, v169
	s_nop 3
	s_lshr_b32 s0, s0, 8
	s_cmp_lg_u32 s0, 0
	s_cbranch_scc0 .Lg1_noprio
	s_setprio 1
.Lg1_noprio:
	s_waitcnt vmcnt(8)
	s_barrier
	ds_read_b128 v[140:143], v186 offset:16384
	ds_read_b128 v[144:147], v186 offset:17408
	ds_read_b128 v[132:135], v186 offset:24576
	ds_read_b128 v[128:131], v186 offset:25600
	ds_read_b128 v[136:139], v184
	ds_read_b128 v[148:151], v184 offset:1024
	ds_read_b128 v[152:155], v184 offset:2048
	ds_read_b128 v[178:181], v184 offset:3072

; #define WAIT_V(n) asm volatile("s_waitcnt vmcnt(" #n ")" ::: "memory")
; #define BAR __builtin_amdgcn_s_barrier()
; #define LDA_(dst, ai) _Pragma("unroll") for (int m = 0; m < 4; ++m) dst[m] = *(const bf16x8*)(sb + (ai) * 8192 + la0 + m * 1024)
; #define LDB_(dst) _Pragma("unroll") for (int bj = 0; bj < 2; ++bj) _Pragma("unroll") for (int n = 0; n < 2; ++n) dst[bj][n] = *(const bf16x8*)(sb + 16384 + bj * 8192 + lb0 + n * 1024)
; #define MMA_(ai, bf_, af_) _Pragma("unroll") for (int bj = 0; bj < 2; ++bj) _Pragma("unroll") for (int m = 0; m < 4; ++m) _Pragma("unroll") for (int n = 0; n < 2; ++n) \
;         acc[ai][bj][m][n] = __builtin_amdgcn_mfma_f32_16x16x32_bf16(bf_[bj][n], af_[m], acc[ai][bj][m][n], 0, 0, 0)
; template <int MODE>
; DI void gemm_phase(const Params& p, int layer, int hf, unsigned char* shmc, int tid) {
;     ...
;     for (int kt = 0; kt < nt; ++kt) {
;       const int rem = nt - 1 - kt;
;       if (rem >= 2) WAIT_V(8); else if (rem == 1) WAIT_V(4); else WAIT_V(0);
;       BAR;
;       const unsigned char* sb = shmc + (kt & 3) * 32768;
;     ...
;       {
;         bf16x8 b0[2][2], a0[4], a1[4];
;         LDB_(b0); LDA_(a0, 0);
;         __builtin_amdgcn_sched_barrier(0);
;         LDA_(a1, 1); MMA_(0, b0, a0);
;         __builtin_amdgcn_sched_barrier(0);
;         if (kt + 3 < nt) STAGE_ALL((kt + 3) & 3, kt + 3);
;         __builtin_amdgcn_sched_barrier(0);
;         MMA_(1, b0, a1);
;       }
;     ...
;     }
.Lg1_nost_3:
	s_waitcnt lgkmcnt(8)
	v_mfma_f32_16x16x32_bf16 v[12:15], v[204:207], v[156:159], v[12:15]
	v_mfma_f32_16x16x32_bf16 v[8:11], v[208:211], v[156:159], v[8:11]
	v_mfma_f32_16x16x32_bf16 v[4:7], v[204:207], v[236:239], v[4:7]
	v_mfma_f32_16x16x32_bf16 v[0:3], v[208:211], v[236:239], v[0:3]
	v_mfma_f32_16x16x32_bf16 v[16:19], v[204:207], v[240:243], v[16:19]
	v_mfma_f32_16x16x32_bf16 v[20:23], v[208:211], v[240:243], v[20:23]
	v_mfma_f32_16x16x32_bf16 v[24:27], v[204:207], v[244:247], v[24:27]
	v_mfma_f32_16x16x32_bf16 v[28:31], v[208:211], v[244:247], v[28:31]
	v_mfma_f32_16x16x32_bf16 v[32:35], v[212:215], v[156:159], v[32:35]
	v_mfma_f32_16x16x32_bf16 v[36:39], v[216:219], v[156:159], v[36:39]
	v_mfma_f32_16x16x32_bf16 v[40:43], v[212:215], v[236:239], v[40:43]
	v_mfma_f32_16x16x32_bf16 v[44:47], v[216:219], v[236:239], v[44:47]
	v_mfma_f32_16x16x32_bf16 v[48:51], v[212:215], v[240:243], v[48:51]
	v_mfma_f32_16x16x32_bf16 v[52:55], v[216:219], v[240:243], v[52:55]
	v_mfma_f32_16x16x32_bf16 v[56:59], v[212:215], v[244:247], v[56:59]
	v_mfma_f32_16x16x32_bf16 v[60:63], v[216:219], v[244:247], v[60:63]
	s_add_i32 s28, s28, 4
	s_cmp_lt_u32 s28, 64
	s_cbranch_scc1 .Lg1_loop
	s_waitcnt lgkmcnt(0)
	s_setprio 0
	v_readlane_b32 s19, v254, 32
